# final elementwise phase software-pipelined (next row's loads in flight during the current row's math)
# speedup vs baseline: 1.0145x; 1.0036x over previous
; __global__ void __launch_bounds__(NWAVES * 64, 2) hymba_fwd(Args args) {
;     ...
;       f32x4 ge[4], bg[4];
; #pragma unroll
;       for (int j = 0; j < 4; ++j) { ge[j] = *(const f32x4*)(args.in[27] + 4 * lane + 256 * j); bg[j] = *(const f32x4*)(args.in[25] + 4 * lane + 256 * j); }
;       for (int m = gw; m < MROWS; m += NGW) { f32x4* xr = (f32x4*)(OUT + (size_t)m * DM) + lane; const v2u* x2r = (const v2u*)(X2B + (size_t)m * DM) + lane; const v2u* er = (const v2u*)(EOUT + (size_t)m * DM) + lane; const v2u* gr = (const v2u*)(GOUT + (size_t)m * DM) + lane;
;         f32x4 v[4], ex[4], gx[4]; float s = 0.f;
; #pragma unroll
;         for (int j = 0; j < 4; ++j) { { const v2u wx = __builtin_nontemporal_load(x2r + 64 * j); v[j] = (f32x4){bflo(wx.x), bfhi(wx.x), bflo(wx.y), bfhi(wx.y)}; } const v2u w = __builtin_nontemporal_load(er + 64 * j); ex[j] = (f32x4){bflo(w.x), bfhi(w.x), bflo(w.y), bfhi(w.y)}; const v2u w2 = __builtin_nontemporal_load(gr + 64 * j); gx[j] = (f32x4){bflo(w2.x), bfhi(w2.x), bflo(w2.y), bfhi(w2.y)};
;           s += (ex[j].x * ex[j].x + ex[j].y * ex[j].y) + (ex[j].z * ex[j].z + ex[j].w * ex[j].w); }
;         const float rs = 1.0f / sqrtf(wave_sum(s) * (1.0f / DM) + EPS);
.LBB0_961:
	s_or_b64 exec, exec, s[0:1]
	s_waitcnt lgkmcnt(0)
	s_barrier
	s_nop 0
	v_readfirstlane_b32 s0, v210
	s_ashr_i32 s0, s0, 6
	s_add_i32 s6, s0, s60
	s_cmp_lt_i32 s6, 0xc000
	s_cbranch_scc0 .LBB0_964
	v_and_b32_e32 v32, 63, v210
	v_readlane_b32 s8, v255, 0
	v_lshlrev_b32_e32 v34, 4, v32
	v_readlane_b32 s14, v255, 6
	v_readlane_b32 s15, v255, 7
	v_readlane_b32 s10, v255, 2
	v_readlane_b32 s11, v255, 3
	s_nop 2
	global_load_dwordx4 v[0:3], v34, s[14:15] offset:3072
	s_nop 0
	global_load_dwordx4 v[4:7], v34, s[10:11] offset:3072
	global_load_dwordx4 v[8:11], v34, s[14:15] offset:2048
	global_load_dwordx4 v[12:15], v34, s[10:11] offset:2048
	global_load_dwordx4 v[16:19], v34, s[14:15] offset:1024
	global_load_dwordx4 v[20:23], v34, s[10:11] offset:1024
	global_load_dwordx4 v[24:27], v34, s[14:15]
	global_load_dwordx4 v[28:31], v34, s[10:11]
	s_ashr_i32 s1, s0, 31
	s_ashr_i32 s2, s60, 31
	s_add_u32 s0, s0, s60
	s_addc_u32 s1, s1, s2
	s_lshl_b64 s[2:3], s[0:1], 11
	s_add_u32 s2, s70, s2
	v_lshlrev_b32_e32 v36, 3, v32
	v_mov_b32_e32 v37, 0
	s_addc_u32 s3, s71, s3
	v_lshl_add_u64 v[32:33], s[2:3], 0, v[36:37]
	s_mov_b64 s[2:3], 0x15a00600
	s_ashr_i32 s35, s34, 31
	v_lshl_add_u64 v[32:33], v[32:33], 0, s[2:3]
	s_lshl_b64 s[2:3], s[34:35], 11
	s_lshl_b64 s[0:1], s[0:1], 12
	s_add_u32 s0, s68, s0
	v_mov_b32_e32 v35, v37
	s_addc_u32 s1, s69, s1
	v_lshl_add_u64 v[34:35], s[0:1], 0, v[34:35]
	s_mov_b64 s[0:1], 0x800
	v_lshl_add_u64 v[34:35], v[34:35], 0, s[0:1]
	s_lshl_b64 s[4:5], s[34:35], 12
	s_mov_b32 s7, 0xfa000000
	v_mov_b32_e32 v44, 0x358637bd
	v_mov_b32_e32 v45, 0x3a800000
	s_mov_b32 s8, 0xf800000
	v_mov_b32_e32 v46, 0x260
	v_readlane_b32 s9, v255, 1
	v_readlane_b32 s12, v255, 4
	v_readlane_b32 s13, v255, 5
	global_load_dwordx2 v[36:37], v[32:33], off offset:-1536 nt
	global_load_dwordx2 v[38:39], v[32:33], off offset:-1024 nt
	global_load_dwordx2 v[40:41], v[32:33], off offset:-512 nt
	global_load_dwordx2 v[42:43], v[32:33], off nt
	v_add_co_u32_e32 v48, vcc, 0xf2500000, v32
	s_nop 0
	s_nop 0
	v_addc_co_u32_e32 v49, vcc, -1, v33, vcc
	v_add_co_u32_e32 v50, vcc, s7, v32
	global_load_dwordx2 v[52:53], v[48:49], off offset:-1536 nt
	global_load_dwordx2 v[54:55], v[48:49], off offset:-1024 nt
	global_load_dwordx2 v[56:57], v[48:49], off offset:-512 nt
	global_load_dwordx2 v[58:59], v[48:49], off nt
	v_addc_co_u32_e32 v51, vcc, -1, v33, vcc
	global_load_dwordx2 v[48:49], v[50:51], off offset:-1536 nt
	global_load_dwordx2 v[60:61], v[50:51], off offset:-1024 nt
	global_load_dwordx2 v[62:63], v[50:51], off offset:-512 nt
	global_load_dwordx2 v[64:65], v[50:51], off nt
	v_lshl_add_u64 v[32:33], v[32:33], 0, s[2:3]
	s_waitcnt vmcnt(0)
.LBB0_963:
	v_mov_b32_e32 v47, 0
	v_mov_b32_e32 v88, 0
	s_add_i32 s6, s6, s34
	s_cmp_gt_i32 s6, 0xbfff
	s_cbranch_scc1 .Lp11_nopf
	global_load_dwordx2 v[100:101], v[32:33], off offset:-1536 nt
	global_load_dwordx2 v[102:103], v[32:33], off offset:-1024 nt
	global_load_dwordx2 v[104:105], v[32:33], off offset:-512 nt
	global_load_dwordx2 v[106:107], v[32:33], off nt
	v_add_co_u32_e32 v124, vcc, 0xf2500000, v32
	s_nop 1
	v_addc_co_u32_e32 v125, vcc, -1, v33, vcc
	v_add_co_u32_e32 v126, vcc, s7, v32
	global_load_dwordx2 v[108:109], v[124:125], off offset:-1536 nt
	global_load_dwordx2 v[110:111], v[124:125], off offset:-1024 nt
	global_load_dwordx2 v[112:113], v[124:125], off offset:-512 nt
	global_load_dwordx2 v[114:115], v[124:125], off nt
	v_addc_co_u32_e32 v127, vcc, -1, v33, vcc
	global_load_dwordx2 v[116:117], v[126:127], off offset:-1536 nt
	global_load_dwordx2 v[118:119], v[126:127], off offset:-1024 nt
	global_load_dwordx2 v[120:121], v[126:127], off offset:-512 nt
	global_load_dwordx2 v[122:123], v[126:127], off nt
	v_lshl_add_u64 v[32:33], v[32:33], 0, s[2:3]
.Lp11_nopf:
	v_lshlrev_b32_e32 v50, 16, v36
	v_and_b32_e32 v51, 0xffff0000, v36
	v_lshlrev_b32_e32 v36, 16, v37
	v_and_b32_e32 v37, 0xffff0000, v37
	v_lshlrev_b32_e32 v66, 16, v38
	v_and_b32_e32 v67, 0xffff0000, v38
	v_lshlrev_b32_e32 v38, 16, v39
	v_and_b32_e32 v39, 0xffff0000, v39
	v_lshlrev_b32_e32 v68, 16, v40
	v_and_b32_e32 v69, 0xffff0000, v40
	v_lshlrev_b32_e32 v40, 16, v41
	v_and_b32_e32 v41, 0xffff0000, v41
	v_mul_f32_e32 v80, v51, v51
	v_mul_f32_e32 v81, v37, v37
	v_mul_f32_e32 v82, v67, v67
	v_mul_f32_e32 v83, v39, v39
	v_lshlrev_b32_e32 v70, 16, v42
	v_and_b32_e32 v71, 0xffff0000, v42
	v_lshlrev_b32_e32 v42, 16, v43
	v_and_b32_e32 v43, 0xffff0000, v43
	v_mul_f32_e32 v84, v69, v69
	v_mul_f32_e32 v85, v41, v41
	v_fmac_f32_e32 v80, v50, v50
	v_fmac_f32_e32 v81, v36, v36
	v_fmac_f32_e32 v82, v66, v66
	v_fmac_f32_e32 v83, v38, v38
	v_mul_f32_e32 v86, v71, v71
	v_mul_f32_e32 v87, v43, v43
	v_fmac_f32_e32 v84, v68, v68
	v_fmac_f32_e32 v85, v40, v40
	v_add_f32_e32 v80, v80, v81
	v_add_f32_e32 v82, v82, v83
	v_fmac_f32_e32 v86, v70, v70
	v_fmac_f32_e32 v87, v42, v42
	v_add_f32_e32 v84, v84, v85
	v_add_f32_e32 v80, v80, v82
	v_add_f32_e32 v86, v86, v87
	v_add_f32_e32 v80, v80, v84
	v_add_f32_e32 v80, v80, v86
	v_lshlrev_b32_e32 v89, 16, v48
	v_lshlrev_b32_e32 v90, 16, v49
	v_lshlrev_b32_e32 v91, 16, v61
	v_lshlrev_b32_e32 v92, 16, v63
	v_lshlrev_b32_e32 v93, 16, v65
	v_add_f32_dpp v80, v80, v80 quad_perm:[1,0,3,2] row_mask:0xf bank_mask:0xf bound_ctrl:1
	v_add_f32_e32 v82, v28, v89
	v_add_f32_e32 v87, v30, v90
	v_add_f32_e32 v89, v22, v91
	v_add_f32_e32 v90, v14, v92
	v_add_f32_e32 v91, v6, v93
	v_add_f32_dpp v80, v80, v80 quad_perm:[2,3,0,1] row_mask:0xf bank_mask:0xf bound_ctrl:1
	v_mul_f32_e32 v84, 0xbfb8aa3b, v87
	v_mul_f32_e32 v87, 0xbfb8aa3b, v89
	v_mul_f32_e32 v89, 0xbfb8aa3b, v90
	v_mul_f32_e32 v90, 0xbfb8aa3b, v91
; __global__ void __launch_bounds__(NWAVES * 64, 2) hymba_fwd(Args args) {
;     ...
;           s += (ex[j].x * ex[j].x + ex[j].y * ex[j].y) + (ex[j].z * ex[j].z + ex[j].w * ex[j].w); }
;         const float rs = 1.0f / sqrtf(wave_sum(s) * (1.0f / DM) + EPS);
; #pragma unroll
;         for (int j = 0; j < 4; ++j) { f32x4 sg;
; #pragma unroll
;           for (int q = 0; q < 4; ++q) sg[q] = __builtin_amdgcn_rcpf(1.0f + __expf(-(gx[j][q] + bg[j][q])));
;           __builtin_nontemporal_store(v[j] + sg * (ex[j] * rs * ge[j]), xr + 64 * j); } } }
	v_add_f32_dpp v80, v80, v80 row_half_mirror row_mask:0xf bank_mask:0xf bound_ctrl:1
	v_exp_f32_e32 v86, v87
	v_exp_f32_e32 v87, v89
	v_exp_f32_e32 v89, v90
	v_add_f32_dpp v90, v80, v80 row_mirror row_mask:0xf bank_mask:0xf bound_ctrl:1
	v_and_b32_e32 v49, 0xffff0000, v49
	v_lshlrev_b32_e32 v85, 16, v64
	v_mov_b32_dpp v47, v90 row_bcast:15 row_mask:0xa bank_mask:0xf
	v_add_f32_e32 v47, v90, v47
	v_and_b32_e32 v64, 0xffff0000, v64
	v_lshlrev_b32_e32 v81, 16, v60
	v_mov_b32_dpp v88, v47 row_bcast:31 row_mask:0xc bank_mask:0xf
	v_add_f32_e32 v47, v47, v88
	v_and_b32_e32 v60, 0xffff0000, v60
	v_readlane_b32 s0, v47, 63
	v_and_b32_e32 v61, 0xffff0000, v61
	v_add_f32_e32 v49, v31, v49
	v_fma_f32 v47, s0, v45, v44
	v_add_f32_e32 v64, v5, v64
	v_mul_f32_e32 v88, 0x4f800000, v47
	v_cmp_gt_f32_e32 vcc, s8, v47
	v_and_b32_e32 v63, 0xffff0000, v63
	v_add_f32_e32 v60, v21, v60
	v_add_f32_e32 v61, v23, v61
	v_mul_f32_e32 v49, 0xbfb8aa3b, v49
	v_mul_f32_e32 v64, 0xbfb8aa3b, v64
	v_cndmask_b32_e32 v47, v47, v88, vcc
	v_add_f32_e32 v63, v15, v63
	v_mul_f32_e32 v60, 0xbfb8aa3b, v60
	v_mul_f32_e32 v61, 0xbfb8aa3b, v61
	v_exp_f32_e32 v49, v49
	v_exp_f32_e32 v64, v64
	v_sqrt_f32_e32 v88, v47
	v_mul_f32_e32 v63, 0xbfb8aa3b, v63
	v_exp_f32_e32 v60, v60
	v_exp_f32_e32 v61, v61
	v_exp_f32_e32 v63, v63
	v_add_f32_e32 v86, 1.0, v86
	v_add_f32_e32 v89, 1.0, v89
	v_add_f32_e32 v91, 1.0, v49
	v_add_f32_e32 v96, 1.0, v64
	v_rcp_f32_e32 v64, v86
	v_rcp_f32_e32 v86, v89
	v_add_u32_e32 v89, -1, v88
	v_add_f32_e32 v92, 1.0, v60
	v_add_f32_e32 v93, 1.0, v61
	v_rcp_f32_e32 v61, v91
	v_add_u32_e32 v90, 1, v88
	v_fma_f32 v91, -v89, v88, v47
	v_add_f32_e32 v95, 1.0, v63
	v_rcp_f32_e32 v63, v92
	v_fma_f32 v92, -v90, v88, v47
	v_cmp_ge_f32_e64 s[0:1], 0, v91
	v_and_b32_e32 v48, 0xffff0000, v48
	v_lshlrev_b32_e32 v83, 16, v62
	v_cndmask_b32_e64 v88, v88, v89, s[0:1]
	v_cmp_lt_f32_e64 s[0:1], 0, v92
	v_and_b32_e32 v62, 0xffff0000, v62
	v_and_b32_e32 v65, 0xffff0000, v65
	v_cndmask_b32_e64 v88, v88, v90, s[0:1]
	v_mul_f32_e32 v89, 0x37800000, v88
	v_cndmask_b32_e32 v88, v88, v89, vcc
	v_cmp_class_f32_e32 vcc, v47, v46
	v_add_f32_e32 v48, v29, v48
	v_add_f32_e32 v81, v20, v81
	v_cndmask_b32_e32 v47, v88, v47, vcc
	v_div_scale_f32 v88, s[0:1], v47, v47, 1.0
	v_rcp_f32_e32 v90, v88
	v_add_f32_e32 v83, v12, v83
	v_add_f32_e32 v62, v13, v62
	v_add_f32_e32 v85, v4, v85
	v_add_f32_e32 v65, v7, v65
	v_mul_f32_e32 v82, 0xbfb8aa3b, v82
	v_mul_f32_e32 v48, 0xbfb8aa3b, v48
	v_fma_f32 v91, -v88, v90, 1.0
	v_mul_f32_e32 v81, 0xbfb8aa3b, v81
	v_mul_f32_e32 v83, 0xbfb8aa3b, v83
	v_mul_f32_e32 v62, 0xbfb8aa3b, v62
	v_mul_f32_e32 v85, 0xbfb8aa3b, v85
	v_mul_f32_e32 v65, 0xbfb8aa3b, v65
	v_exp_f32_e32 v82, v82
	v_exp_f32_e32 v48, v48
	v_exp_f32_e32 v84, v84
	v_div_scale_f32 v89, vcc, 1.0, v47, 1.0
	v_fmac_f32_e32 v90, v91, v90
	v_exp_f32_e32 v81, v81
	v_exp_f32_e32 v83, v83
	v_exp_f32_e32 v62, v62
	v_exp_f32_e32 v85, v85
	v_exp_f32_e32 v65, v65
	v_mul_f32_e32 v91, v89, v90
	v_fma_f32 v92, -v88, v91, v89
	v_fmac_f32_e32 v91, v92, v90
	v_add_f32_e32 v80, 1.0, v82
	v_add_f32_e32 v82, 1.0, v48
	v_add_f32_e32 v84, 1.0, v84
	v_fma_f32 v88, -v88, v91, v89
	v_add_f32_e32 v81, 1.0, v81
	v_add_f32_e32 v83, 1.0, v83
	v_add_f32_e32 v94, 1.0, v62
	v_add_f32_e32 v87, 1.0, v87
	v_add_f32_e32 v85, 1.0, v85
	v_add_f32_e32 v97, 1.0, v65
	v_rcp_f32_e32 v48, v80
	v_rcp_f32_e32 v49, v82
	v_rcp_f32_e32 v60, v84
	v_div_fmas_f32 v88, v88, v90, v91
	v_rcp_f32_e32 v62, v81
	v_rcp_f32_e32 v65, v93
	v_rcp_f32_e32 v80, v83
	v_rcp_f32_e32 v81, v94
	v_rcp_f32_e32 v82, v87
	v_rcp_f32_e32 v83, v95
	v_rcp_f32_e32 v84, v85
	v_rcp_f32_e32 v85, v96
	v_rcp_f32_e32 v87, v97
	v_div_fixup_f32 v88, v88, v47, 1.0
	v_pk_mul_f32 v[36:37], v[88:89], v[36:37] op_sel_hi:[0,1]
	v_pk_mul_f32 v[50:51], v[88:89], v[50:51] op_sel_hi:[0,1]
	v_lshlrev_b32_e32 v72, 16, v52
	v_and_b32_e32 v73, 0xffff0000, v52
	v_lshlrev_b32_e32 v52, 16, v53
	v_and_b32_e32 v53, 0xffff0000, v53
	v_pk_mul_f32 v[38:39], v[88:89], v[38:39] op_sel_hi:[0,1]
	v_pk_mul_f32 v[66:67], v[88:89], v[66:67] op_sel_hi:[0,1]
	v_pk_mul_f32 v[40:41], v[88:89], v[40:41] op_sel_hi:[0,1]
	v_pk_mul_f32 v[68:69], v[88:89], v[68:69] op_sel_hi:[0,1]
	v_pk_mul_f32 v[42:43], v[88:89], v[42:43] op_sel_hi:[0,1]
	v_pk_mul_f32 v[70:71], v[88:89], v[70:71] op_sel_hi:[0,1]
	v_pk_mul_f32 v[50:51], v[50:51], v[24:25]
	v_pk_mul_f32 v[36:37], v[36:37], v[26:27]
	v_lshlrev_b32_e32 v74, 16, v54
	v_and_b32_e32 v75, 0xffff0000, v54
	v_lshlrev_b32_e32 v54, 16, v55
	v_and_b32_e32 v55, 0xffff0000, v55
	v_lshlrev_b32_e32 v76, 16, v56
	v_and_b32_e32 v77, 0xffff0000, v56
	v_lshlrev_b32_e32 v56, 16, v57
	v_and_b32_e32 v57, 0xffff0000, v57
	v_lshlrev_b32_e32 v78, 16, v58
	v_and_b32_e32 v79, 0xffff0000, v58
	v_lshlrev_b32_e32 v58, 16, v59
	v_and_b32_e32 v59, 0xffff0000, v59
	v_pk_mul_f32 v[66:67], v[66:67], v[16:17]
	v_pk_mul_f32 v[88:89], v[38:39], v[18:19]
	v_pk_mul_f32 v[68:69], v[68:69], v[8:9]
	v_pk_mul_f32 v[90:91], v[40:41], v[10:11]
	v_pk_mul_f32 v[70:71], v[70:71], v[0:1]
	v_pk_mul_f32 v[92:93], v[42:43], v[2:3]
	v_pk_fma_f32 v[38:39], v[60:61], v[36:37], v[52:53]
	v_pk_fma_f32 v[36:37], v[48:49], v[50:51], v[72:73]
	v_pk_fma_f32 v[42:43], v[64:65], v[88:89], v[54:55]
	v_pk_fma_f32 v[40:41], v[62:63], v[66:67], v[74:75]
	v_pk_fma_f32 v[50:51], v[82:83], v[90:91], v[56:57]
	v_pk_fma_f32 v[48:49], v[80:81], v[68:69], v[76:77]
	v_pk_fma_f32 v[54:55], v[86:87], v[92:93], v[58:59]
	v_pk_fma_f32 v[52:53], v[84:85], v[70:71], v[78:79]
	global_store_dwordx4 v[34:35], v[36:39], off offset:-2048 nt
	global_store_dwordx4 v[34:35], v[40:43], off offset:-1024 nt
	global_store_dwordx4 v[34:35], v[48:51], off nt
	global_store_dwordx4 v[34:35], v[52:55], off offset:1024 nt
	v_lshl_add_u64 v[34:35], v[34:35], 0, s[4:5]
	s_cbranch_scc1 .LBB0_964
	s_waitcnt vmcnt(4)
	s_nop 0
	v_mov_b64_e32 v[36:37], v[100:101]
	v_mov_b64_e32 v[38:39], v[102:103]
	v_mov_b64_e32 v[40:41], v[104:105]
	v_mov_b64_e32 v[42:43], v[106:107]
	v_mov_b64_e32 v[52:53], v[108:109]
	v_mov_b64_e32 v[54:55], v[110:111]
	v_mov_b64_e32 v[56:57], v[112:113]
	v_mov_b64_e32 v[58:59], v[114:115]
	v_mov_b64_e32 v[48:49], v[116:117]
	v_mov_b64_e32 v[60:61], v[118:119]
	v_mov_b64_e32 v[62:63], v[120:121]
	v_mov_b64_e32 v[64:65], v[122:123]
	s_branch .LBB0_963
